# RMS epilogue row-statistics exchange: no L1 invalidate after the counter spin (slots are read with device-scope loads)
# speedup vs baseline: 1.0255x; 1.0007x over previous
;     __device__ __forceinline__ void stats(const f32x4 (&v)[2][2][4][2], const Unit& u, int wr, int wc, int fr, int fq, LAS unsigned char* lds, int wid, int lane, const RmsX& e) const {
;     ...
;         if (wid == 0) { unsigned sp = 0;
;             while ((unsigned)__builtin_amdgcn_readfirstlane(__hip_atomic_load(e.cnt + 64 * u.pm, __ATOMIC_RELAXED, __HIP_MEMORY_SCOPE_AGENT)) < e.target) { __builtin_amdgcn_s_sleep(2); if (++sp > (1u << 22)) break; }
;             __builtin_amdgcn_fence(__ATOMIC_ACQUIRE, "agent"); }
;         asm volatile("s_waitcnt vmcnt(0) lgkmcnt(0)" ::: "memory"); __builtin_amdgcn_s_barrier(); asm volatile("" ::: "memory");
;         if (lane < 32) { const unsigned* sl = (const unsigned*)(e.slots + (size_t)(u.pm * BM + row) * 4); float t = 0.f;
; #pragma unroll
;             for (int k = 0; k < 4; ++k) t += __uint_as_float(__hip_atomic_load(sl + k, __ATOMIC_RELAXED, __HIP_MEMORY_SCOPE_AGENT));
;             S[row] = rsqrtf(t * (1.f / 1024.f) + EPS); }
.LBB0_253:
	s_waitcnt lgkmcnt(0)
.LBB0_254:
	s_waitcnt vmcnt(0) lgkmcnt(0)
	s_barrier
	s_lshl_b32 s0, s18, 8
	v_add_u32_e32 v0, s0, v174
	s_waitcnt lgkmcnt(0)
	v_ashrrev_i32_e32 v1, 31, v0
	s_and_saveexec_b64 s[30:31], s[6:7]
	s_cbranch_execz .LBB0_256
	v_lshl_add_u64 v[132:133], v[0:1], 4, s[14:15]
	global_load_dword v134, v[132:133], off sc1
	global_load_dword v135, v[132:133], off offset:4 sc1
	global_load_dword v140, v[132:133], off offset:8 sc1
	s_nop 0
	global_load_dword v132, v[132:133], off offset:12 sc1
	s_waitcnt vmcnt(3)
	v_add_f32_e32 v134, 0, v134
	s_waitcnt vmcnt(2)
	v_add_f32_e32 v134, v134, v135
	s_waitcnt vmcnt(1)
	v_add_f32_e32 v134, v134, v140
	s_waitcnt vmcnt(0)
	v_add_f32_e32 v132, v134, v132
	v_fmamk_f32 v132, v132, 0x3a800000, v204
	v_cmp_gt_f32_e32 vcc, s93, v132
	v_mul_f32_e32 v133, 0x4b800000, v132
	s_nop 0
	v_cndmask_b32_e32 v132, v132, v133, vcc
	v_rsq_f32_e32 v132, v132
	s_nop 0
	v_mul_f32_e32 v133, 0x45800000, v132
	v_cndmask_b32_e32 v132, v132, v133, vcc
	v_lshl_add_u32 v133, v174, 2, 0
	ds_write_b32 v133, v132 offset:4096

;     __device__ __forceinline__ void stats(const f32x4 (&v)[2][2][4][2], const Unit& u, int wr, int wc, int fr, int fq, LAS unsigned char* lds, int wid, int lane, const RmsX& e) const {
;     ...
;         if (wid == 0) { unsigned sp = 0;
;             while ((unsigned)__builtin_amdgcn_readfirstlane(__hip_atomic_load(e.cnt + 64 * u.pm, __ATOMIC_RELAXED, __HIP_MEMORY_SCOPE_AGENT)) < e.target) { __builtin_amdgcn_s_sleep(2); if (++sp > (1u << 22)) break; }
;             __builtin_amdgcn_fence(__ATOMIC_ACQUIRE, "agent"); }
;         asm volatile("s_waitcnt vmcnt(0) lgkmcnt(0)" ::: "memory"); __builtin_amdgcn_s_barrier(); asm volatile("" ::: "memory");
;         if (lane < 32) { const unsigned* sl = (const unsigned*)(e.slots + (size_t)(u.pm * BM + row) * 4); float t = 0.f;
; #pragma unroll
;             for (int k = 0; k < 4; ++k) t += __uint_as_float(__hip_atomic_load(sl + k, __ATOMIC_RELAXED, __HIP_MEMORY_SCOPE_AGENT));
;             S[row] = rsqrtf(t * (1.f / 1024.f) + EPS); }
.LBB0_287:
	s_waitcnt lgkmcnt(0)
.LBB0_288:
	s_waitcnt vmcnt(0) lgkmcnt(0)
	s_barrier
	s_and_saveexec_b64 s[8:9], s[6:7]
	s_cbranch_execz .LBB0_290
	v_lshl_add_u64 v[0:1], v[0:1], 4, s[4:5]
	global_load_dword v132, v[0:1], off sc1
	global_load_dword v133, v[0:1], off offset:4 sc1
	global_load_dword v134, v[0:1], off offset:8 sc1
	s_nop 0
	global_load_dword v0, v[0:1], off offset:12 sc1
	s_waitcnt vmcnt(3)
	v_add_f32_e32 v1, 0, v132
	s_waitcnt vmcnt(2)
	v_add_f32_e32 v1, v1, v133
	s_waitcnt vmcnt(1)
	v_add_f32_e32 v1, v1, v134
	s_waitcnt vmcnt(0)
	v_add_f32_e32 v0, v1, v0
	v_fmamk_f32 v0, v0, 0x3a800000, v204
	v_mul_f32_e32 v1, 0x4b800000, v0
	v_cmp_gt_f32_e32 vcc, s93, v0
	s_nop 1
	v_cndmask_b32_e32 v0, v0, v1, vcc
	v_rsq_f32_e32 v0, v0
	s_nop 0
	v_mul_f32_e32 v1, 0x45800000, v0
	v_cndmask_b32_e32 v0, v0, v1, vcc
	v_lshl_add_u32 v1, v174, 2, 0
	ds_write_b32 v1, v0 offset:4096

;     __device__ __forceinline__ void stats(const f32x4 (&v)[2][2][4][2], const Unit& u, int wr, int wc, int fr, int fq, LAS unsigned char* lds, int wid, int lane, const RmsX& e) const {
;     ...
;         if (wid == 0) { unsigned sp = 0;
;             while ((unsigned)__builtin_amdgcn_readfirstlane(__hip_atomic_load(e.cnt + 64 * u.pm, __ATOMIC_RELAXED, __HIP_MEMORY_SCOPE_AGENT)) < e.target) { __builtin_amdgcn_s_sleep(2); if (++sp > (1u << 22)) break; }
;             __builtin_amdgcn_fence(__ATOMIC_ACQUIRE, "agent"); }
;         asm volatile("s_waitcnt vmcnt(0) lgkmcnt(0)" ::: "memory"); __builtin_amdgcn_s_barrier(); asm volatile("" ::: "memory");
;         if (lane < 32) { const unsigned* sl = (const unsigned*)(e.slots + (size_t)(u.pm * BM + row) * 4); float t = 0.f;
; #pragma unroll
;             for (int k = 0; k < 4; ++k) t += __uint_as_float(__hip_atomic_load(sl + k, __ATOMIC_RELAXED, __HIP_MEMORY_SCOPE_AGENT));
;             S[row] = rsqrtf(t * (1.f / 1024.f) + EPS); }
.LBB0_487:
	s_waitcnt lgkmcnt(0)
.LBB0_488:
	s_waitcnt vmcnt(0) lgkmcnt(0)
	s_barrier
	s_lshl_b32 s41, s35, 8
	v_add_u32_e32 v146, s41, v161
	v_ashrrev_i32_e32 v147, 31, v146
	s_and_saveexec_b64 s[10:11], s[6:7]
	s_cbranch_execz .LBB0_490
	s_waitcnt lgkmcnt(0)
	v_lshl_add_u64 v[0:1], v[146:147], 4, s[12:13]
	global_load_dword v132, v[0:1], off sc1
	global_load_dword v133, v[0:1], off offset:4 sc1
	global_load_dword v134, v[0:1], off offset:8 sc1
	s_nop 0
	global_load_dword v0, v[0:1], off offset:12 sc1
	s_waitcnt vmcnt(3)
	v_add_f32_e32 v132, 0, v132
	s_waitcnt vmcnt(2)
	v_add_f32_e32 v132, v132, v133
	s_waitcnt vmcnt(1)
	v_add_f32_e32 v132, v132, v134
	s_waitcnt vmcnt(0)
	v_add_f32_e32 v0, v132, v0
	v_fmamk_f32 v0, v0, 0x3a800000, v204
	v_cmp_gt_f32_e32 vcc, s93, v0
	v_mul_f32_e32 v1, 0x4b800000, v0
	s_nop 0
	v_cndmask_b32_e32 v0, v0, v1, vcc
	v_rsq_f32_e32 v0, v0
	s_nop 0
	v_mul_f32_e32 v1, 0x45800000, v0
	v_cndmask_b32_e32 v0, v0, v1, vcc
	v_lshl_add_u32 v1, v161, 2, 0
	ds_write_b32 v1, v0 offset:4096

;     __device__ __forceinline__ void stats(const f32x4 (&v)[2][2][4][2], const Unit& u, int wr, int wc, int fr, int fq, LAS unsigned char* lds, int wid, int lane, const RmsX& e) const {
;     ...
;         if (wid == 0) { unsigned sp = 0;
;             while ((unsigned)__builtin_amdgcn_readfirstlane(__hip_atomic_load(e.cnt + 64 * u.pm, __ATOMIC_RELAXED, __HIP_MEMORY_SCOPE_AGENT)) < e.target) { __builtin_amdgcn_s_sleep(2); if (++sp > (1u << 22)) break; }
;             __builtin_amdgcn_fence(__ATOMIC_ACQUIRE, "agent"); }
;         asm volatile("s_waitcnt vmcnt(0) lgkmcnt(0)" ::: "memory"); __builtin_amdgcn_s_barrier(); asm volatile("" ::: "memory");
;         if (lane < 32) { const unsigned* sl = (const unsigned*)(e.slots + (size_t)(u.pm * BM + row) * 4); float t = 0.f;
; #pragma unroll
;             for (int k = 0; k < 4; ++k) t += __uint_as_float(__hip_atomic_load(sl + k, __ATOMIC_RELAXED, __HIP_MEMORY_SCOPE_AGENT));
;             S[row] = rsqrtf(t * (1.f / 1024.f) + EPS); }
.LBB0_587:
	s_waitcnt lgkmcnt(0)
.LBB0_588:
	s_waitcnt vmcnt(0) lgkmcnt(0)
	s_barrier
	s_and_saveexec_b64 s[8:9], s[6:7]
	s_cbranch_execz .LBB0_590
	v_lshl_add_u64 v[132:133], v[146:147], 4, s[4:5]
	global_load_dword v134, v[132:133], off sc1
	global_load_dword v135, v[132:133], off offset:4 sc1
	global_load_dword v140, v[132:133], off offset:8 sc1
	s_nop 0
	global_load_dword v132, v[132:133], off offset:12 sc1
	s_waitcnt vmcnt(3)
	v_add_f32_e32 v133, 0, v134
	s_waitcnt vmcnt(2)
	v_add_f32_e32 v133, v133, v135
	s_waitcnt vmcnt(1)
	v_add_f32_e32 v133, v133, v140
	s_waitcnt vmcnt(0)
	v_add_f32_e32 v132, v133, v132
	v_fmamk_f32 v132, v132, 0x3a800000, v204
	v_mul_f32_e32 v133, 0x4b800000, v132
	v_cmp_gt_f32_e32 vcc, s93, v132
	s_nop 1
	v_cndmask_b32_e32 v132, v132, v133, vcc
	v_rsq_f32_e32 v132, v132
	s_nop 0
	v_mul_f32_e32 v133, 0x45800000, v132
	v_cndmask_b32_e32 v132, v132, v133, vcc
	v_lshl_add_u32 v133, v161, 2, 0
	ds_write_b32 v133, v132 offset:4096
